# prep unit (gated short conv) rewritten by hand: 16 tokens of loads in flight instead of one
# speedup vs baseline: 1.2499x; 1.0109x over previous
.LBB0_265:
	s_and_b64 vcc, exec, s[0:1]
	s_cbranch_vccz .LBB0_268
	v_lshlrev_b32_e32 v64, 2, v163
	v_lshlrev_b32_e32 v66, 3, v163
	v_readlane_b32 s0, v235, 12
	v_readlane_b32 s1, v235, 13
	s_add_i32 s4, s6, 0xffffff80
	s_mul_i32 s5, s4, 0xcc000
	s_mul_hi_u32 s7, s4, 0xcc000
	s_nop 1
	global_load_dwordx2 v[50:51], v66, s[0:1]
	global_load_dwordx2 v[52:53], v66, s[0:1] offset:2048
	s_add_u32 s2, s0, 0x1000
	s_addc_u32 s3, s1, 0
	global_load_dwordx2 v[54:55], v66, s[2:3]
	s_add_u32 s0, s78, s5
	s_addc_u32 s1, s79, s7
	s_and_b32 s5, s4, 63
	s_cmp_eq_u32 s5, 0
	s_cbranch_scc1 .Lpp_nohist
	s_add_u32 s2, s0, 0xffff9a00
	s_addc_u32 s3, s1, -1
	global_load_dword v60, v64, s[2:3] offset:2048
	global_load_dword v61, v64, s[2:3] offset:3072
	s_add_u32 s2, s0, 0xffffcd00
	s_addc_u32 s3, s1, -1
	global_load_dword v62, v64, s[2:3] offset:2048
	global_load_dword v63, v64, s[2:3] offset:3072
	s_branch .Lpp_hist
.Lpp_nohist:
	v_mov_b32_e32 v60, 0
	v_mov_b32_e32 v61, 0
	v_mov_b32_e32 v62, 0
	v_mov_b32_e32 v63, 0
.Lpp_hist:
	s_mul_i32 s5, s4, 0x12000
	s_mul_hi_u32 s7, s4, 0x12000
	s_add_u32 s2, s84, s5
	s_addc_u32 s3, s85, s7
	global_load_dword v2, v64, s[0:1] offset:1024
	global_load_dword v3, v64, s[0:1] offset:2048
	global_load_dword v4, v64, s[0:1] offset:3072
	s_add_u32 s0, s0, 0x3300
	s_addc_u32 s1, s1, 0
	global_load_dword v5, v64, s[0:1] offset:1024
	global_load_dword v6, v64, s[0:1] offset:2048
	global_load_dword v7, v64, s[0:1] offset:3072
	s_add_u32 s0, s0, 0x3300
	s_addc_u32 s1, s1, 0
	global_load_dword v8, v64, s[0:1] offset:1024
	global_load_dword v9, v64, s[0:1] offset:2048
	global_load_dword v10, v64, s[0:1] offset:3072
	s_add_u32 s0, s0, 0x3300
	s_addc_u32 s1, s1, 0
	global_load_dword v11, v64, s[0:1] offset:1024
	global_load_dword v12, v64, s[0:1] offset:2048
	global_load_dword v13, v64, s[0:1] offset:3072
	s_add_u32 s0, s0, 0x3300
	s_addc_u32 s1, s1, 0
	global_load_dword v14, v64, s[0:1] offset:1024
	global_load_dword v15, v64, s[0:1] offset:2048
	global_load_dword v16, v64, s[0:1] offset:3072
	s_add_u32 s0, s0, 0x3300
	s_addc_u32 s1, s1, 0
	global_load_dword v17, v64, s[0:1] offset:1024
	global_load_dword v18, v64, s[0:1] offset:2048
	global_load_dword v19, v64, s[0:1] offset:3072
	s_add_u32 s0, s0, 0x3300
	s_addc_u32 s1, s1, 0
	global_load_dword v20, v64, s[0:1] offset:1024
	global_load_dword v21, v64, s[0:1] offset:2048
	global_load_dword v22, v64, s[0:1] offset:3072
	s_add_u32 s0, s0, 0x3300
	s_addc_u32 s1, s1, 0
	global_load_dword v23, v64, s[0:1] offset:1024
	global_load_dword v24, v64, s[0:1] offset:2048
	global_load_dword v25, v64, s[0:1] offset:3072
	s_add_u32 s0, s0, 0x3300
	s_addc_u32 s1, s1, 0
	global_load_dword v26, v64, s[0:1] offset:1024
	global_load_dword v27, v64, s[0:1] offset:2048
	global_load_dword v28, v64, s[0:1] offset:3072
	s_add_u32 s0, s0, 0x3300
	s_addc_u32 s1, s1, 0
	global_load_dword v29, v64, s[0:1] offset:1024
	global_load_dword v30, v64, s[0:1] offset:2048
	global_load_dword v31, v64, s[0:1] offset:3072
	s_add_u32 s0, s0, 0x3300
	s_addc_u32 s1, s1, 0
	global_load_dword v32, v64, s[0:1] offset:1024
	global_load_dword v33, v64, s[0:1] offset:2048
	global_load_dword v34, v64, s[0:1] offset:3072
	s_add_u32 s0, s0, 0x3300
	s_addc_u32 s1, s1, 0
	global_load_dword v35, v64, s[0:1] offset:1024
	global_load_dword v36, v64, s[0:1] offset:2048
	global_load_dword v37, v64, s[0:1] offset:3072
	s_add_u32 s0, s0, 0x3300
	s_addc_u32 s1, s1, 0
	global_load_dword v38, v64, s[0:1] offset:1024
	global_load_dword v39, v64, s[0:1] offset:2048
	global_load_dword v40, v64, s[0:1] offset:3072
	s_add_u32 s0, s0, 0x3300
	s_addc_u32 s1, s1, 0
	global_load_dword v41, v64, s[0:1] offset:1024
	global_load_dword v42, v64, s[0:1] offset:2048
	global_load_dword v43, v64, s[0:1] offset:3072
	s_add_u32 s0, s0, 0x3300
	s_addc_u32 s1, s1, 0
	global_load_dword v44, v64, s[0:1] offset:1024
	global_load_dword v45, v64, s[0:1] offset:2048
	global_load_dword v46, v64, s[0:1] offset:3072
	s_add_u32 s0, s0, 0x3300
	s_addc_u32 s1, s1, 0
	global_load_dword v47, v64, s[0:1] offset:1024
	global_load_dword v48, v64, s[0:1] offset:2048
	global_load_dword v49, v64, s[0:1] offset:3072
	s_add_u32 s0, s0, 0x3300
	s_addc_u32 s1, s1, 0
	s_waitcnt vmcnt(48)
	v_lshlrev_b32_e32 v66, 16, v60
	v_lshlrev_b32_e32 v67, 16, v61
	v_and_b32_e32 v68, 0xffff0000, v60
	v_and_b32_e32 v69, 0xffff0000, v61
	v_mul_f32_e32 v56, v66, v67
	v_mul_f32_e32 v57, v68, v69
	v_lshlrev_b32_e32 v66, 16, v62
	v_lshlrev_b32_e32 v67, 16, v63
	v_and_b32_e32 v68, 0xffff0000, v62
	v_and_b32_e32 v69, 0xffff0000, v63
	v_mul_f32_e32 v58, v66, v67
	v_mul_f32_e32 v59, v68, v69
	s_waitcnt vmcnt(24)
	v_lshlrev_b32_e32 v68, 16, v3
	v_and_b32_e32 v69, 0xffff0000, v3
	v_lshlrev_b32_e32 v70, 16, v4
	v_and_b32_e32 v71, 0xffff0000, v4
	v_lshlrev_b32_e32 v66, 16, v2
	v_and_b32_e32 v67, 0xffff0000, v2
	v_mul_f32_e32 v3, v68, v70
	v_mul_f32_e32 v4, v69, v71
	v_mul_f32_e32 v74, v52, v58
	v_mul_f32_e32 v75, v53, v59
	v_mul_f32_e32 v76, v54, v3
	v_mul_f32_e32 v77, v55, v4
	v_fma_f32 v74, v50, v56, v74
	v_fma_f32 v75, v51, v57, v75
	v_add_f32_e32 v74, v74, v76
	v_add_f32_e32 v75, v75, v77
	v_mul_f32_e32 v74, v74, v66
	v_mul_f32_e32 v75, v75, v67
	v_cvt_pk_bf16_f32 v2, v74, v75
	global_store_dword v64, v2, s[2:3]
	s_add_u32 s2, s2, 0x480
	s_addc_u32 s3, s3, 0
	v_lshlrev_b32_e32 v68, 16, v6
	v_and_b32_e32 v69, 0xffff0000, v6
	v_lshlrev_b32_e32 v70, 16, v7
	v_and_b32_e32 v71, 0xffff0000, v7
	v_lshlrev_b32_e32 v66, 16, v5
	v_and_b32_e32 v67, 0xffff0000, v5
	v_mul_f32_e32 v6, v68, v70
	v_mul_f32_e32 v7, v69, v71
	v_mul_f32_e32 v74, v52, v3
	v_mul_f32_e32 v75, v53, v4
	v_mul_f32_e32 v76, v54, v6
	v_mul_f32_e32 v77, v55, v7
	v_fma_f32 v74, v50, v58, v74
	v_fma_f32 v75, v51, v59, v75
	v_add_f32_e32 v74, v74, v76
	v_add_f32_e32 v75, v75, v77
	v_mul_f32_e32 v74, v74, v66
	v_mul_f32_e32 v75, v75, v67
	v_cvt_pk_bf16_f32 v5, v74, v75
	global_store_dword v64, v5, s[2:3]
	s_add_u32 s2, s2, 0x480
	s_addc_u32 s3, s3, 0
	v_lshlrev_b32_e32 v68, 16, v9
	v_and_b32_e32 v69, 0xffff0000, v9
	v_lshlrev_b32_e32 v70, 16, v10
	v_and_b32_e32 v71, 0xffff0000, v10
	v_lshlrev_b32_e32 v66, 16, v8
	v_and_b32_e32 v67, 0xffff0000, v8
	v_mul_f32_e32 v9, v68, v70
	v_mul_f32_e32 v10, v69, v71
	v_mul_f32_e32 v74, v52, v6
	v_mul_f32_e32 v75, v53, v7
	v_mul_f32_e32 v76, v54, v9
	v_mul_f32_e32 v77, v55, v10
	v_fma_f32 v74, v50, v3, v74
	v_fma_f32 v75, v51, v4, v75
	v_add_f32_e32 v74, v74, v76
	v_add_f32_e32 v75, v75, v77
	v_mul_f32_e32 v74, v74, v66
	v_mul_f32_e32 v75, v75, v67
	v_cvt_pk_bf16_f32 v8, v74, v75
	global_store_dword v64, v8, s[2:3]
	s_add_u32 s2, s2, 0x480
	s_addc_u32 s3, s3, 0
	v_lshlrev_b32_e32 v68, 16, v12
	v_and_b32_e32 v69, 0xffff0000, v12
	v_lshlrev_b32_e32 v70, 16, v13
	v_and_b32_e32 v71, 0xffff0000, v13
	v_lshlrev_b32_e32 v66, 16, v11
	v_and_b32_e32 v67, 0xffff0000, v11
	v_mul_f32_e32 v12, v68, v70
	v_mul_f32_e32 v13, v69, v71
	v_mul_f32_e32 v74, v52, v9
	v_mul_f32_e32 v75, v53, v10
	v_mul_f32_e32 v76, v54, v12
	v_mul_f32_e32 v77, v55, v13
	v_fma_f32 v74, v50, v6, v74
	v_fma_f32 v75, v51, v7, v75
	v_add_f32_e32 v74, v74, v76
	v_add_f32_e32 v75, v75, v77
	v_mul_f32_e32 v74, v74, v66
	v_mul_f32_e32 v75, v75, v67
	v_cvt_pk_bf16_f32 v11, v74, v75
	global_store_dword v64, v11, s[2:3]
	s_add_u32 s2, s2, 0x480
	s_addc_u32 s3, s3, 0
	v_lshlrev_b32_e32 v68, 16, v15
	v_and_b32_e32 v69, 0xffff0000, v15
	v_lshlrev_b32_e32 v70, 16, v16
	v_and_b32_e32 v71, 0xffff0000, v16
	v_lshlrev_b32_e32 v66, 16, v14
	v_and_b32_e32 v67, 0xffff0000, v14
	v_mul_f32_e32 v15, v68, v70
	v_mul_f32_e32 v16, v69, v71
	v_mul_f32_e32 v74, v52, v12
	v_mul_f32_e32 v75, v53, v13
	v_mul_f32_e32 v76, v54, v15
	v_mul_f32_e32 v77, v55, v16
	v_fma_f32 v74, v50, v9, v74
	v_fma_f32 v75, v51, v10, v75
	v_add_f32_e32 v74, v74, v76
	v_add_f32_e32 v75, v75, v77
	v_mul_f32_e32 v74, v74, v66
	v_mul_f32_e32 v75, v75, v67
	v_cvt_pk_bf16_f32 v14, v74, v75
	global_store_dword v64, v14, s[2:3]
	s_add_u32 s2, s2, 0x480
	s_addc_u32 s3, s3, 0
	v_lshlrev_b32_e32 v68, 16, v18
	v_and_b32_e32 v69, 0xffff0000, v18
	v_lshlrev_b32_e32 v70, 16, v19
	v_and_b32_e32 v71, 0xffff0000, v19
	v_lshlrev_b32_e32 v66, 16, v17
	v_and_b32_e32 v67, 0xffff0000, v17
	v_mul_f32_e32 v18, v68, v70
	v_mul_f32_e32 v19, v69, v71
	v_mul_f32_e32 v74, v52, v15
	v_mul_f32_e32 v75, v53, v16
	v_mul_f32_e32 v76, v54, v18
	v_mul_f32_e32 v77, v55, v19
	v_fma_f32 v74, v50, v12, v74
	v_fma_f32 v75, v51, v13, v75
	v_add_f32_e32 v74, v74, v76
	v_add_f32_e32 v75, v75, v77
	v_mul_f32_e32 v74, v74, v66
	v_mul_f32_e32 v75, v75, v67
	v_cvt_pk_bf16_f32 v17, v74, v75
	global_store_dword v64, v17, s[2:3]
	s_add_u32 s2, s2, 0x480
	s_addc_u32 s3, s3, 0
	v_lshlrev_b32_e32 v68, 16, v21
	v_and_b32_e32 v69, 0xffff0000, v21
	v_lshlrev_b32_e32 v70, 16, v22
	v_and_b32_e32 v71, 0xffff0000, v22
	v_lshlrev_b32_e32 v66, 16, v20
	v_and_b32_e32 v67, 0xffff0000, v20
	v_mul_f32_e32 v21, v68, v70
	v_mul_f32_e32 v22, v69, v71
	v_mul_f32_e32 v74, v52, v18
	v_mul_f32_e32 v75, v53, v19
	v_mul_f32_e32 v76, v54, v21
	v_mul_f32_e32 v77, v55, v22
	v_fma_f32 v74, v50, v15, v74
	v_fma_f32 v75, v51, v16, v75
	v_add_f32_e32 v74, v74, v76
	v_add_f32_e32 v75, v75, v77
	v_mul_f32_e32 v74, v74, v66
	v_mul_f32_e32 v75, v75, v67
	v_cvt_pk_bf16_f32 v20, v74, v75
	global_store_dword v64, v20, s[2:3]
	s_add_u32 s2, s2, 0x480
	s_addc_u32 s3, s3, 0
	v_lshlrev_b32_e32 v68, 16, v24
	v_and_b32_e32 v69, 0xffff0000, v24
	v_lshlrev_b32_e32 v70, 16, v25
	v_and_b32_e32 v71, 0xffff0000, v25
	v_lshlrev_b32_e32 v66, 16, v23
	v_and_b32_e32 v67, 0xffff0000, v23
	v_mul_f32_e32 v24, v68, v70
	v_mul_f32_e32 v25, v69, v71
	v_mul_f32_e32 v74, v52, v21
	v_mul_f32_e32 v75, v53, v22
	v_mul_f32_e32 v76, v54, v24
	v_mul_f32_e32 v77, v55, v25
	v_fma_f32 v74, v50, v18, v74
	v_fma_f32 v75, v51, v19, v75
	v_add_f32_e32 v74, v74, v76
	v_add_f32_e32 v75, v75, v77
	v_mul_f32_e32 v74, v74, v66
	v_mul_f32_e32 v75, v75, v67
	v_cvt_pk_bf16_f32 v23, v74, v75
	global_store_dword v64, v23, s[2:3]
	s_add_u32 s2, s2, 0x480
	s_addc_u32 s3, s3, 0
	v_mov_b32_e32 v56, v21
	v_mov_b32_e32 v57, v22
	v_mov_b32_e32 v58, v24
	v_mov_b32_e32 v59, v25
	global_load_dword v2, v64, s[0:1] offset:1024
	global_load_dword v3, v64, s[0:1] offset:2048
	global_load_dword v4, v64, s[0:1] offset:3072
	s_add_u32 s0, s0, 0x3300
	s_addc_u32 s1, s1, 0
	global_load_dword v5, v64, s[0:1] offset:1024
	global_load_dword v6, v64, s[0:1] offset:2048
	global_load_dword v7, v64, s[0:1] offset:3072
	s_add_u32 s0, s0, 0x3300
	s_addc_u32 s1, s1, 0
	global_load_dword v8, v64, s[0:1] offset:1024
	global_load_dword v9, v64, s[0:1] offset:2048
	global_load_dword v10, v64, s[0:1] offset:3072
	s_add_u32 s0, s0, 0x3300
	s_addc_u32 s1, s1, 0
	global_load_dword v11, v64, s[0:1] offset:1024
	global_load_dword v12, v64, s[0:1] offset:2048
	global_load_dword v13, v64, s[0:1] offset:3072
	s_add_u32 s0, s0, 0x3300
	s_addc_u32 s1, s1, 0
	global_load_dword v14, v64, s[0:1] offset:1024
	global_load_dword v15, v64, s[0:1] offset:2048
	global_load_dword v16, v64, s[0:1] offset:3072
	s_add_u32 s0, s0, 0x3300
	s_addc_u32 s1, s1, 0
	global_load_dword v17, v64, s[0:1] offset:1024
	global_load_dword v18, v64, s[0:1] offset:2048
	global_load_dword v19, v64, s[0:1] offset:3072
	s_add_u32 s0, s0, 0x3300
	s_addc_u32 s1, s1, 0
	global_load_dword v20, v64, s[0:1] offset:1024
	global_load_dword v21, v64, s[0:1] offset:2048
	global_load_dword v22, v64, s[0:1] offset:3072
	s_add_u32 s0, s0, 0x3300
	s_addc_u32 s1, s1, 0
	global_load_dword v23, v64, s[0:1] offset:1024
	global_load_dword v24, v64, s[0:1] offset:2048
	global_load_dword v25, v64, s[0:1] offset:3072
	s_add_u32 s0, s0, 0x3300
	s_addc_u32 s1, s1, 0
	s_waitcnt vmcnt(32)
	v_lshlrev_b32_e32 v68, 16, v27
	v_and_b32_e32 v69, 0xffff0000, v27
	v_lshlrev_b32_e32 v70, 16, v28
	v_and_b32_e32 v71, 0xffff0000, v28
	v_lshlrev_b32_e32 v66, 16, v26
	v_and_b32_e32 v67, 0xffff0000, v26
	v_mul_f32_e32 v27, v68, v70
	v_mul_f32_e32 v28, v69, v71
	v_mul_f32_e32 v74, v52, v58
	v_mul_f32_e32 v75, v53, v59
	v_mul_f32_e32 v76, v54, v27
	v_mul_f32_e32 v77, v55, v28
	v_fma_f32 v74, v50, v56, v74
	v_fma_f32 v75, v51, v57, v75
	v_add_f32_e32 v74, v74, v76
	v_add_f32_e32 v75, v75, v77
	v_mul_f32_e32 v74, v74, v66
	v_mul_f32_e32 v75, v75, v67
	v_cvt_pk_bf16_f32 v26, v74, v75
	global_store_dword v64, v26, s[2:3]
	s_add_u32 s2, s2, 0x480
	s_addc_u32 s3, s3, 0
	v_lshlrev_b32_e32 v68, 16, v30
	v_and_b32_e32 v69, 0xffff0000, v30
	v_lshlrev_b32_e32 v70, 16, v31
	v_and_b32_e32 v71, 0xffff0000, v31
	v_lshlrev_b32_e32 v66, 16, v29
	v_and_b32_e32 v67, 0xffff0000, v29
	v_mul_f32_e32 v30, v68, v70
	v_mul_f32_e32 v31, v69, v71
	v_mul_f32_e32 v74, v52, v27
	v_mul_f32_e32 v75, v53, v28
	v_mul_f32_e32 v76, v54, v30
	v_mul_f32_e32 v77, v55, v31
	v_fma_f32 v74, v50, v58, v74
	v_fma_f32 v75, v51, v59, v75
	v_add_f32_e32 v74, v74, v76
	v_add_f32_e32 v75, v75, v77
	v_mul_f32_e32 v74, v74, v66
	v_mul_f32_e32 v75, v75, v67
	v_cvt_pk_bf16_f32 v29, v74, v75
	global_store_dword v64, v29, s[2:3]
	s_add_u32 s2, s2, 0x480
	s_addc_u32 s3, s3, 0
	v_lshlrev_b32_e32 v68, 16, v33
	v_and_b32_e32 v69, 0xffff0000, v33
	v_lshlrev_b32_e32 v70, 16, v34
	v_and_b32_e32 v71, 0xffff0000, v34
	v_lshlrev_b32_e32 v66, 16, v32
	v_and_b32_e32 v67, 0xffff0000, v32
	v_mul_f32_e32 v33, v68, v70
	v_mul_f32_e32 v34, v69, v71
	v_mul_f32_e32 v74, v52, v30
	v_mul_f32_e32 v75, v53, v31
	v_mul_f32_e32 v76, v54, v33
	v_mul_f32_e32 v77, v55, v34
	v_fma_f32 v74, v50, v27, v74
	v_fma_f32 v75, v51, v28, v75
	v_add_f32_e32 v74, v74, v76
	v_add_f32_e32 v75, v75, v77
	v_mul_f32_e32 v74, v74, v66
	v_mul_f32_e32 v75, v75, v67
	v_cvt_pk_bf16_f32 v32, v74, v75
	global_store_dword v64, v32, s[2:3]
	s_add_u32 s2, s2, 0x480
	s_addc_u32 s3, s3, 0
	v_lshlrev_b32_e32 v68, 16, v36
	v_and_b32_e32 v69, 0xffff0000, v36
	v_lshlrev_b32_e32 v70, 16, v37
	v_and_b32_e32 v71, 0xffff0000, v37
	v_lshlrev_b32_e32 v66, 16, v35
	v_and_b32_e32 v67, 0xffff0000, v35
	v_mul_f32_e32 v36, v68, v70
	v_mul_f32_e32 v37, v69, v71
	v_mul_f32_e32 v74, v52, v33
	v_mul_f32_e32 v75, v53, v34
	v_mul_f32_e32 v76, v54, v36
	v_mul_f32_e32 v77, v55, v37
	v_fma_f32 v74, v50, v30, v74
	v_fma_f32 v75, v51, v31, v75
	v_add_f32_e32 v74, v74, v76
	v_add_f32_e32 v75, v75, v77
	v_mul_f32_e32 v74, v74, v66
	v_mul_f32_e32 v75, v75, v67
	v_cvt_pk_bf16_f32 v35, v74, v75
	global_store_dword v64, v35, s[2:3]
	s_add_u32 s2, s2, 0x480
	s_addc_u32 s3, s3, 0
	v_lshlrev_b32_e32 v68, 16, v39
	v_and_b32_e32 v69, 0xffff0000, v39
	v_lshlrev_b32_e32 v70, 16, v40
	v_and_b32_e32 v71, 0xffff0000, v40
	v_lshlrev_b32_e32 v66, 16, v38
	v_and_b32_e32 v67, 0xffff0000, v38
	v_mul_f32_e32 v39, v68, v70
	v_mul_f32_e32 v40, v69, v71
	v_mul_f32_e32 v74, v52, v36
	v_mul_f32_e32 v75, v53, v37
	v_mul_f32_e32 v76, v54, v39
	v_mul_f32_e32 v77, v55, v40
	v_fma_f32 v74, v50, v33, v74
	v_fma_f32 v75, v51, v34, v75
	v_add_f32_e32 v74, v74, v76
	v_add_f32_e32 v75, v75, v77
	v_mul_f32_e32 v74, v74, v66
	v_mul_f32_e32 v75, v75, v67
	v_cvt_pk_bf16_f32 v38, v74, v75
	global_store_dword v64, v38, s[2:3]
	s_add_u32 s2, s2, 0x480
	s_addc_u32 s3, s3, 0
	v_lshlrev_b32_e32 v68, 16, v42
	v_and_b32_e32 v69, 0xffff0000, v42
	v_lshlrev_b32_e32 v70, 16, v43
	v_and_b32_e32 v71, 0xffff0000, v43
	v_lshlrev_b32_e32 v66, 16, v41
	v_and_b32_e32 v67, 0xffff0000, v41
	v_mul_f32_e32 v42, v68, v70
	v_mul_f32_e32 v43, v69, v71
	v_mul_f32_e32 v74, v52, v39
	v_mul_f32_e32 v75, v53, v40
	v_mul_f32_e32 v76, v54, v42
	v_mul_f32_e32 v77, v55, v43
	v_fma_f32 v74, v50, v36, v74
	v_fma_f32 v75, v51, v37, v75
	v_add_f32_e32 v74, v74, v76
	v_add_f32_e32 v75, v75, v77
	v_mul_f32_e32 v74, v74, v66
	v_mul_f32_e32 v75, v75, v67
	v_cvt_pk_bf16_f32 v41, v74, v75
	global_store_dword v64, v41, s[2:3]
	s_add_u32 s2, s2, 0x480
	s_addc_u32 s3, s3, 0
	v_lshlrev_b32_e32 v68, 16, v45
	v_and_b32_e32 v69, 0xffff0000, v45
	v_lshlrev_b32_e32 v70, 16, v46
	v_and_b32_e32 v71, 0xffff0000, v46
	v_lshlrev_b32_e32 v66, 16, v44
	v_and_b32_e32 v67, 0xffff0000, v44
	v_mul_f32_e32 v45, v68, v70
	v_mul_f32_e32 v46, v69, v71
	v_mul_f32_e32 v74, v52, v42
	v_mul_f32_e32 v75, v53, v43
	v_mul_f32_e32 v76, v54, v45
	v_mul_f32_e32 v77, v55, v46
	v_fma_f32 v74, v50, v39, v74
	v_fma_f32 v75, v51, v40, v75
	v_add_f32_e32 v74, v74, v76
	v_add_f32_e32 v75, v75, v77
	v_mul_f32_e32 v74, v74, v66
	v_mul_f32_e32 v75, v75, v67
	v_cvt_pk_bf16_f32 v44, v74, v75
	global_store_dword v64, v44, s[2:3]
	s_add_u32 s2, s2, 0x480
	s_addc_u32 s3, s3, 0
	v_lshlrev_b32_e32 v68, 16, v48
	v_and_b32_e32 v69, 0xffff0000, v48
	v_lshlrev_b32_e32 v70, 16, v49
	v_and_b32_e32 v71, 0xffff0000, v49
	v_lshlrev_b32_e32 v66, 16, v47
	v_and_b32_e32 v67, 0xffff0000, v47
	v_mul_f32_e32 v48, v68, v70
	v_mul_f32_e32 v49, v69, v71
	v_mul_f32_e32 v74, v52, v45
	v_mul_f32_e32 v75, v53, v46
	v_mul_f32_e32 v76, v54, v48
	v_mul_f32_e32 v77, v55, v49
	v_fma_f32 v74, v50, v42, v74
	v_fma_f32 v75, v51, v43, v75
	v_add_f32_e32 v74, v74, v76
	v_add_f32_e32 v75, v75, v77
	v_mul_f32_e32 v74, v74, v66
	v_mul_f32_e32 v75, v75, v67
	v_cvt_pk_bf16_f32 v47, v74, v75
	global_store_dword v64, v47, s[2:3]
	s_add_u32 s2, s2, 0x480
	s_addc_u32 s3, s3, 0
	v_mov_b32_e32 v56, v45
	v_mov_b32_e32 v57, v46
	v_mov_b32_e32 v58, v48
	v_mov_b32_e32 v59, v49
	global_load_dword v26, v64, s[0:1] offset:1024
	global_load_dword v27, v64, s[0:1] offset:2048
	global_load_dword v28, v64, s[0:1] offset:3072
	s_add_u32 s0, s0, 0x3300
	s_addc_u32 s1, s1, 0
	global_load_dword v29, v64, s[0:1] offset:1024
	global_load_dword v30, v64, s[0:1] offset:2048
	global_load_dword v31, v64, s[0:1] offset:3072
	s_add_u32 s0, s0, 0x3300
	s_addc_u32 s1, s1, 0
	global_load_dword v32, v64, s[0:1] offset:1024
	global_load_dword v33, v64, s[0:1] offset:2048
	global_load_dword v34, v64, s[0:1] offset:3072
	s_add_u32 s0, s0, 0x3300
	s_addc_u32 s1, s1, 0
	global_load_dword v35, v64, s[0:1] offset:1024
	global_load_dword v36, v64, s[0:1] offset:2048
	global_load_dword v37, v64, s[0:1] offset:3072
	s_add_u32 s0, s0, 0x3300
	s_addc_u32 s1, s1, 0
	global_load_dword v38, v64, s[0:1] offset:1024
	global_load_dword v39, v64, s[0:1] offset:2048
	global_load_dword v40, v64, s[0:1] offset:3072
	s_add_u32 s0, s0, 0x3300
	s_addc_u32 s1, s1, 0
	global_load_dword v41, v64, s[0:1] offset:1024
	global_load_dword v42, v64, s[0:1] offset:2048
	global_load_dword v43, v64, s[0:1] offset:3072
	s_add_u32 s0, s0, 0x3300
	s_addc_u32 s1, s1, 0
	global_load_dword v44, v64, s[0:1] offset:1024
	global_load_dword v45, v64, s[0:1] offset:2048
	global_load_dword v46, v64, s[0:1] offset:3072
	s_add_u32 s0, s0, 0x3300
	s_addc_u32 s1, s1, 0
	global_load_dword v47, v64, s[0:1] offset:1024
	global_load_dword v48, v64, s[0:1] offset:2048
	global_load_dword v49, v64, s[0:1] offset:3072
	s_add_u32 s0, s0, 0x3300
	s_addc_u32 s1, s1, 0
	s_waitcnt vmcnt(32)
	v_lshlrev_b32_e32 v68, 16, v3
	v_and_b32_e32 v69, 0xffff0000, v3
	v_lshlrev_b32_e32 v70, 16, v4
	v_and_b32_e32 v71, 0xffff0000, v4
	v_lshlrev_b32_e32 v66, 16, v2
	v_and_b32_e32 v67, 0xffff0000, v2
	v_mul_f32_e32 v3, v68, v70
	v_mul_f32_e32 v4, v69, v71
	v_mul_f32_e32 v74, v52, v58
	v_mul_f32_e32 v75, v53, v59
	v_mul_f32_e32 v76, v54, v3
	v_mul_f32_e32 v77, v55, v4
	v_fma_f32 v74, v50, v56, v74
	v_fma_f32 v75, v51, v57, v75
	v_add_f32_e32 v74, v74, v76
	v_add_f32_e32 v75, v75, v77
	v_mul_f32_e32 v74, v74, v66
	v_mul_f32_e32 v75, v75, v67
	v_cvt_pk_bf16_f32 v2, v74, v75
	global_store_dword v64, v2, s[2:3]
	s_add_u32 s2, s2, 0x480
	s_addc_u32 s3, s3, 0
	v_lshlrev_b32_e32 v68, 16, v6
	v_and_b32_e32 v69, 0xffff0000, v6
	v_lshlrev_b32_e32 v70, 16, v7
	v_and_b32_e32 v71, 0xffff0000, v7
	v_lshlrev_b32_e32 v66, 16, v5
	v_and_b32_e32 v67, 0xffff0000, v5
	v_mul_f32_e32 v6, v68, v70
	v_mul_f32_e32 v7, v69, v71
	v_mul_f32_e32 v74, v52, v3
	v_mul_f32_e32 v75, v53, v4
	v_mul_f32_e32 v76, v54, v6
	v_mul_f32_e32 v77, v55, v7
	v_fma_f32 v74, v50, v58, v74
	v_fma_f32 v75, v51, v59, v75
	v_add_f32_e32 v74, v74, v76
	v_add_f32_e32 v75, v75, v77
	v_mul_f32_e32 v74, v74, v66
	v_mul_f32_e32 v75, v75, v67
	v_cvt_pk_bf16_f32 v5, v74, v75
	global_store_dword v64, v5, s[2:3]
	s_add_u32 s2, s2, 0x480
	s_addc_u32 s3, s3, 0
	v_lshlrev_b32_e32 v68, 16, v9
	v_and_b32_e32 v69, 0xffff0000, v9
	v_lshlrev_b32_e32 v70, 16, v10
	v_and_b32_e32 v71, 0xffff0000, v10
	v_lshlrev_b32_e32 v66, 16, v8
	v_and_b32_e32 v67, 0xffff0000, v8
	v_mul_f32_e32 v9, v68, v70
	v_mul_f32_e32 v10, v69, v71
	v_mul_f32_e32 v74, v52, v6
	v_mul_f32_e32 v75, v53, v7
	v_mul_f32_e32 v76, v54, v9
	v_mul_f32_e32 v77, v55, v10
	v_fma_f32 v74, v50, v3, v74
	v_fma_f32 v75, v51, v4, v75
	v_add_f32_e32 v74, v74, v76
	v_add_f32_e32 v75, v75, v77
	v_mul_f32_e32 v74, v74, v66
	v_mul_f32_e32 v75, v75, v67
	v_cvt_pk_bf16_f32 v8, v74, v75
	global_store_dword v64, v8, s[2:3]
	s_add_u32 s2, s2, 0x480
	s_addc_u32 s3, s3, 0
	v_lshlrev_b32_e32 v68, 16, v12
	v_and_b32_e32 v69, 0xffff0000, v12
	v_lshlrev_b32_e32 v70, 16, v13
	v_and_b32_e32 v71, 0xffff0000, v13
	v_lshlrev_b32_e32 v66, 16, v11
	v_and_b32_e32 v67, 0xffff0000, v11
	v_mul_f32_e32 v12, v68, v70
	v_mul_f32_e32 v13, v69, v71
	v_mul_f32_e32 v74, v52, v9
	v_mul_f32_e32 v75, v53, v10
	v_mul_f32_e32 v76, v54, v12
	v_mul_f32_e32 v77, v55, v13
	v_fma_f32 v74, v50, v6, v74
	v_fma_f32 v75, v51, v7, v75
	v_add_f32_e32 v74, v74, v76
	v_add_f32_e32 v75, v75, v77
	v_mul_f32_e32 v74, v74, v66
	v_mul_f32_e32 v75, v75, v67
	v_cvt_pk_bf16_f32 v11, v74, v75
	global_store_dword v64, v11, s[2:3]
	s_add_u32 s2, s2, 0x480
	s_addc_u32 s3, s3, 0
	v_lshlrev_b32_e32 v68, 16, v15
	v_and_b32_e32 v69, 0xffff0000, v15
	v_lshlrev_b32_e32 v70, 16, v16
	v_and_b32_e32 v71, 0xffff0000, v16
	v_lshlrev_b32_e32 v66, 16, v14
	v_and_b32_e32 v67, 0xffff0000, v14
	v_mul_f32_e32 v15, v68, v70
	v_mul_f32_e32 v16, v69, v71
	v_mul_f32_e32 v74, v52, v12
	v_mul_f32_e32 v75, v53, v13
	v_mul_f32_e32 v76, v54, v15
	v_mul_f32_e32 v77, v55, v16
	v_fma_f32 v74, v50, v9, v74
	v_fma_f32 v75, v51, v10, v75
	v_add_f32_e32 v74, v74, v76
	v_add_f32_e32 v75, v75, v77
	v_mul_f32_e32 v74, v74, v66
	v_mul_f32_e32 v75, v75, v67
	v_cvt_pk_bf16_f32 v14, v74, v75
	global_store_dword v64, v14, s[2:3]
	s_add_u32 s2, s2, 0x480
	s_addc_u32 s3, s3, 0
	v_lshlrev_b32_e32 v68, 16, v18
	v_and_b32_e32 v69, 0xffff0000, v18
	v_lshlrev_b32_e32 v70, 16, v19
	v_and_b32_e32 v71, 0xffff0000, v19
	v_lshlrev_b32_e32 v66, 16, v17
	v_and_b32_e32 v67, 0xffff0000, v17
	v_mul_f32_e32 v18, v68, v70
	v_mul_f32_e32 v19, v69, v71
	v_mul_f32_e32 v74, v52, v15
	v_mul_f32_e32 v75, v53, v16
	v_mul_f32_e32 v76, v54, v18
	v_mul_f32_e32 v77, v55, v19
	v_fma_f32 v74, v50, v12, v74
	v_fma_f32 v75, v51, v13, v75
	v_add_f32_e32 v74, v74, v76
	v_add_f32_e32 v75, v75, v77
	v_mul_f32_e32 v74, v74, v66
	v_mul_f32_e32 v75, v75, v67
	v_cvt_pk_bf16_f32 v17, v74, v75
	global_store_dword v64, v17, s[2:3]
	s_add_u32 s2, s2, 0x480
	s_addc_u32 s3, s3, 0
	v_lshlrev_b32_e32 v68, 16, v21
	v_and_b32_e32 v69, 0xffff0000, v21
	v_lshlrev_b32_e32 v70, 16, v22
	v_and_b32_e32 v71, 0xffff0000, v22
	v_lshlrev_b32_e32 v66, 16, v20
	v_and_b32_e32 v67, 0xffff0000, v20
	v_mul_f32_e32 v21, v68, v70
	v_mul_f32_e32 v22, v69, v71
	v_mul_f32_e32 v74, v52, v18
	v_mul_f32_e32 v75, v53, v19
	v_mul_f32_e32 v76, v54, v21
	v_mul_f32_e32 v77, v55, v22
	v_fma_f32 v74, v50, v15, v74
	v_fma_f32 v75, v51, v16, v75
	v_add_f32_e32 v74, v74, v76
	v_add_f32_e32 v75, v75, v77
	v_mul_f32_e32 v74, v74, v66
	v_mul_f32_e32 v75, v75, v67
	v_cvt_pk_bf16_f32 v20, v74, v75
	global_store_dword v64, v20, s[2:3]
	s_add_u32 s2, s2, 0x480
	s_addc_u32 s3, s3, 0
	v_lshlrev_b32_e32 v68, 16, v24
	v_and_b32_e32 v69, 0xffff0000, v24
	v_lshlrev_b32_e32 v70, 16, v25
	v_and_b32_e32 v71, 0xffff0000, v25
	v_lshlrev_b32_e32 v66, 16, v23
	v_and_b32_e32 v67, 0xffff0000, v23
	v_mul_f32_e32 v24, v68, v70
	v_mul_f32_e32 v25, v69, v71
	v_mul_f32_e32 v74, v52, v21
	v_mul_f32_e32 v75, v53, v22
	v_mul_f32_e32 v76, v54, v24
	v_mul_f32_e32 v77, v55, v25
	v_fma_f32 v74, v50, v18, v74
	v_fma_f32 v75, v51, v19, v75
	v_add_f32_e32 v74, v74, v76
	v_add_f32_e32 v75, v75, v77
	v_mul_f32_e32 v74, v74, v66
	v_mul_f32_e32 v75, v75, v67
	v_cvt_pk_bf16_f32 v23, v74, v75
	global_store_dword v64, v23, s[2:3]
	s_add_u32 s2, s2, 0x480
	s_addc_u32 s3, s3, 0
	v_mov_b32_e32 v56, v21
	v_mov_b32_e32 v57, v22
	v_mov_b32_e32 v58, v24
	v_mov_b32_e32 v59, v25
	global_load_dword v2, v64, s[0:1] offset:1024
	global_load_dword v3, v64, s[0:1] offset:2048
	global_load_dword v4, v64, s[0:1] offset:3072
	s_add_u32 s0, s0, 0x3300
	s_addc_u32 s1, s1, 0
	global_load_dword v5, v64, s[0:1] offset:1024
	global_load_dword v6, v64, s[0:1] offset:2048
	global_load_dword v7, v64, s[0:1] offset:3072
	s_add_u32 s0, s0, 0x3300
	s_addc_u32 s1, s1, 0
	global_load_dword v8, v64, s[0:1] offset:1024
	global_load_dword v9, v64, s[0:1] offset:2048
	global_load_dword v10, v64, s[0:1] offset:3072
	s_add_u32 s0, s0, 0x3300
	s_addc_u32 s1, s1, 0
	global_load_dword v11, v64, s[0:1] offset:1024
	global_load_dword v12, v64, s[0:1] offset:2048
	global_load_dword v13, v64, s[0:1] offset:3072
	s_add_u32 s0, s0, 0x3300
	s_addc_u32 s1, s1, 0
	global_load_dword v14, v64, s[0:1] offset:1024
	global_load_dword v15, v64, s[0:1] offset:2048
	global_load_dword v16, v64, s[0:1] offset:3072
	s_add_u32 s0, s0, 0x3300
	s_addc_u32 s1, s1, 0
	global_load_dword v17, v64, s[0:1] offset:1024
	global_load_dword v18, v64, s[0:1] offset:2048
	global_load_dword v19, v64, s[0:1] offset:3072
	s_add_u32 s0, s0, 0x3300
	s_addc_u32 s1, s1, 0
	global_load_dword v20, v64, s[0:1] offset:1024
	global_load_dword v21, v64, s[0:1] offset:2048
	global_load_dword v22, v64, s[0:1] offset:3072
	s_add_u32 s0, s0, 0x3300
	s_addc_u32 s1, s1, 0
	global_load_dword v23, v64, s[0:1] offset:1024
	global_load_dword v24, v64, s[0:1] offset:2048
	global_load_dword v25, v64, s[0:1] offset:3072
	s_add_u32 s0, s0, 0x3300
	s_addc_u32 s1, s1, 0
	s_waitcnt vmcnt(32)
	v_lshlrev_b32_e32 v68, 16, v27
	v_and_b32_e32 v69, 0xffff0000, v27
	v_lshlrev_b32_e32 v70, 16, v28
	v_and_b32_e32 v71, 0xffff0000, v28
	v_lshlrev_b32_e32 v66, 16, v26
	v_and_b32_e32 v67, 0xffff0000, v26
	v_mul_f32_e32 v27, v68, v70
	v_mul_f32_e32 v28, v69, v71
	v_mul_f32_e32 v74, v52, v58
	v_mul_f32_e32 v75, v53, v59
	v_mul_f32_e32 v76, v54, v27
	v_mul_f32_e32 v77, v55, v28
	v_fma_f32 v74, v50, v56, v74
	v_fma_f32 v75, v51, v57, v75
	v_add_f32_e32 v74, v74, v76
	v_add_f32_e32 v75, v75, v77
	v_mul_f32_e32 v74, v74, v66
	v_mul_f32_e32 v75, v75, v67
	v_cvt_pk_bf16_f32 v26, v74, v75
	global_store_dword v64, v26, s[2:3]
	s_add_u32 s2, s2, 0x480
	s_addc_u32 s3, s3, 0
	v_lshlrev_b32_e32 v68, 16, v30
	v_and_b32_e32 v69, 0xffff0000, v30
	v_lshlrev_b32_e32 v70, 16, v31
	v_and_b32_e32 v71, 0xffff0000, v31
	v_lshlrev_b32_e32 v66, 16, v29
	v_and_b32_e32 v67, 0xffff0000, v29
	v_mul_f32_e32 v30, v68, v70
	v_mul_f32_e32 v31, v69, v71
	v_mul_f32_e32 v74, v52, v27
	v_mul_f32_e32 v75, v53, v28
	v_mul_f32_e32 v76, v54, v30
	v_mul_f32_e32 v77, v55, v31
	v_fma_f32 v74, v50, v58, v74
	v_fma_f32 v75, v51, v59, v75
	v_add_f32_e32 v74, v74, v76
	v_add_f32_e32 v75, v75, v77
	v_mul_f32_e32 v74, v74, v66
	v_mul_f32_e32 v75, v75, v67
	v_cvt_pk_bf16_f32 v29, v74, v75
	global_store_dword v64, v29, s[2:3]
	s_add_u32 s2, s2, 0x480
	s_addc_u32 s3, s3, 0
	v_lshlrev_b32_e32 v68, 16, v33
	v_and_b32_e32 v69, 0xffff0000, v33
	v_lshlrev_b32_e32 v70, 16, v34
	v_and_b32_e32 v71, 0xffff0000, v34
	v_lshlrev_b32_e32 v66, 16, v32
	v_and_b32_e32 v67, 0xffff0000, v32
	v_mul_f32_e32 v33, v68, v70
	v_mul_f32_e32 v34, v69, v71
	v_mul_f32_e32 v74, v52, v30
	v_mul_f32_e32 v75, v53, v31
	v_mul_f32_e32 v76, v54, v33
	v_mul_f32_e32 v77, v55, v34
	v_fma_f32 v74, v50, v27, v74
	v_fma_f32 v75, v51, v28, v75
	v_add_f32_e32 v74, v74, v76
	v_add_f32_e32 v75, v75, v77
	v_mul_f32_e32 v74, v74, v66
	v_mul_f32_e32 v75, v75, v67
	v_cvt_pk_bf16_f32 v32, v74, v75
	global_store_dword v64, v32, s[2:3]
	s_add_u32 s2, s2, 0x480
	s_addc_u32 s3, s3, 0
	v_lshlrev_b32_e32 v68, 16, v36
	v_and_b32_e32 v69, 0xffff0000, v36
	v_lshlrev_b32_e32 v70, 16, v37
	v_and_b32_e32 v71, 0xffff0000, v37
	v_lshlrev_b32_e32 v66, 16, v35
	v_and_b32_e32 v67, 0xffff0000, v35
	v_mul_f32_e32 v36, v68, v70
	v_mul_f32_e32 v37, v69, v71
	v_mul_f32_e32 v74, v52, v33
	v_mul_f32_e32 v75, v53, v34
	v_mul_f32_e32 v76, v54, v36
	v_mul_f32_e32 v77, v55, v37
	v_fma_f32 v74, v50, v30, v74
	v_fma_f32 v75, v51, v31, v75
	v_add_f32_e32 v74, v74, v76
	v_add_f32_e32 v75, v75, v77
	v_mul_f32_e32 v74, v74, v66
	v_mul_f32_e32 v75, v75, v67
	v_cvt_pk_bf16_f32 v35, v74, v75
	global_store_dword v64, v35, s[2:3]
	s_add_u32 s2, s2, 0x480
	s_addc_u32 s3, s3, 0
	v_lshlrev_b32_e32 v68, 16, v39
	v_and_b32_e32 v69, 0xffff0000, v39
	v_lshlrev_b32_e32 v70, 16, v40
	v_and_b32_e32 v71, 0xffff0000, v40
	v_lshlrev_b32_e32 v66, 16, v38
	v_and_b32_e32 v67, 0xffff0000, v38
	v_mul_f32_e32 v39, v68, v70
	v_mul_f32_e32 v40, v69, v71
	v_mul_f32_e32 v74, v52, v36
	v_mul_f32_e32 v75, v53, v37
	v_mul_f32_e32 v76, v54, v39
	v_mul_f32_e32 v77, v55, v40
	v_fma_f32 v74, v50, v33, v74
	v_fma_f32 v75, v51, v34, v75
	v_add_f32_e32 v74, v74, v76
	v_add_f32_e32 v75, v75, v77
	v_mul_f32_e32 v74, v74, v66
	v_mul_f32_e32 v75, v75, v67
	v_cvt_pk_bf16_f32 v38, v74, v75
	global_store_dword v64, v38, s[2:3]
	s_add_u32 s2, s2, 0x480
	s_addc_u32 s3, s3, 0
	v_lshlrev_b32_e32 v68, 16, v42
	v_and_b32_e32 v69, 0xffff0000, v42
	v_lshlrev_b32_e32 v70, 16, v43
	v_and_b32_e32 v71, 0xffff0000, v43
	v_lshlrev_b32_e32 v66, 16, v41
	v_and_b32_e32 v67, 0xffff0000, v41
	v_mul_f32_e32 v42, v68, v70
	v_mul_f32_e32 v43, v69, v71
	v_mul_f32_e32 v74, v52, v39
	v_mul_f32_e32 v75, v53, v40
	v_mul_f32_e32 v76, v54, v42
	v_mul_f32_e32 v77, v55, v43
	v_fma_f32 v74, v50, v36, v74
	v_fma_f32 v75, v51, v37, v75
	v_add_f32_e32 v74, v74, v76
	v_add_f32_e32 v75, v75, v77
	v_mul_f32_e32 v74, v74, v66
	v_mul_f32_e32 v75, v75, v67
	v_cvt_pk_bf16_f32 v41, v74, v75
	global_store_dword v64, v41, s[2:3]
	s_add_u32 s2, s2, 0x480
	s_addc_u32 s3, s3, 0
	v_lshlrev_b32_e32 v68, 16, v45
	v_and_b32_e32 v69, 0xffff0000, v45
	v_lshlrev_b32_e32 v70, 16, v46
	v_and_b32_e32 v71, 0xffff0000, v46
	v_lshlrev_b32_e32 v66, 16, v44
	v_and_b32_e32 v67, 0xffff0000, v44
	v_mul_f32_e32 v45, v68, v70
	v_mul_f32_e32 v46, v69, v71
	v_mul_f32_e32 v74, v52, v42
	v_mul_f32_e32 v75, v53, v43
	v_mul_f32_e32 v76, v54, v45
	v_mul_f32_e32 v77, v55, v46
	v_fma_f32 v74, v50, v39, v74
	v_fma_f32 v75, v51, v40, v75
	v_add_f32_e32 v74, v74, v76
	v_add_f32_e32 v75, v75, v77
	v_mul_f32_e32 v74, v74, v66
	v_mul_f32_e32 v75, v75, v67
	v_cvt_pk_bf16_f32 v44, v74, v75
	global_store_dword v64, v44, s[2:3]
	s_add_u32 s2, s2, 0x480
	s_addc_u32 s3, s3, 0
	v_lshlrev_b32_e32 v68, 16, v48
	v_and_b32_e32 v69, 0xffff0000, v48
	v_lshlrev_b32_e32 v70, 16, v49
	v_and_b32_e32 v71, 0xffff0000, v49
	v_lshlrev_b32_e32 v66, 16, v47
	v_and_b32_e32 v67, 0xffff0000, v47
	v_mul_f32_e32 v48, v68, v70
	v_mul_f32_e32 v49, v69, v71
	v_mul_f32_e32 v74, v52, v45
	v_mul_f32_e32 v75, v53, v46
	v_mul_f32_e32 v76, v54, v48
	v_mul_f32_e32 v77, v55, v49
	v_fma_f32 v74, v50, v42, v74
	v_fma_f32 v75, v51, v43, v75
	v_add_f32_e32 v74, v74, v76
	v_add_f32_e32 v75, v75, v77
	v_mul_f32_e32 v74, v74, v66
	v_mul_f32_e32 v75, v75, v67
	v_cvt_pk_bf16_f32 v47, v74, v75
	global_store_dword v64, v47, s[2:3]
	s_add_u32 s2, s2, 0x480
	s_addc_u32 s3, s3, 0
	v_mov_b32_e32 v56, v45
	v_mov_b32_e32 v57, v46
	v_mov_b32_e32 v58, v48
	v_mov_b32_e32 v59, v49
	global_load_dword v26, v64, s[0:1] offset:1024
	global_load_dword v27, v64, s[0:1] offset:2048
	global_load_dword v28, v64, s[0:1] offset:3072
	s_add_u32 s0, s0, 0x3300
	s_addc_u32 s1, s1, 0
	global_load_dword v29, v64, s[0:1] offset:1024
	global_load_dword v30, v64, s[0:1] offset:2048
	global_load_dword v31, v64, s[0:1] offset:3072
	s_add_u32 s0, s0, 0x3300
	s_addc_u32 s1, s1, 0
	global_load_dword v32, v64, s[0:1] offset:1024
	global_load_dword v33, v64, s[0:1] offset:2048
	global_load_dword v34, v64, s[0:1] offset:3072
	s_add_u32 s0, s0, 0x3300
	s_addc_u32 s1, s1, 0
	global_load_dword v35, v64, s[0:1] offset:1024
	global_load_dword v36, v64, s[0:1] offset:2048
	global_load_dword v37, v64, s[0:1] offset:3072
	s_add_u32 s0, s0, 0x3300
	s_addc_u32 s1, s1, 0
	global_load_dword v38, v64, s[0:1] offset:1024
	global_load_dword v39, v64, s[0:1] offset:2048
	global_load_dword v40, v64, s[0:1] offset:3072
	s_add_u32 s0, s0, 0x3300
	s_addc_u32 s1, s1, 0
	global_load_dword v41, v64, s[0:1] offset:1024
	global_load_dword v42, v64, s[0:1] offset:2048
	global_load_dword v43, v64, s[0:1] offset:3072
	s_add_u32 s0, s0, 0x3300
	s_addc_u32 s1, s1, 0
	global_load_dword v44, v64, s[0:1] offset:1024
	global_load_dword v45, v64, s[0:1] offset:2048
	global_load_dword v46, v64, s[0:1] offset:3072
	s_add_u32 s0, s0, 0x3300
	s_addc_u32 s1, s1, 0
	global_load_dword v47, v64, s[0:1] offset:1024
	global_load_dword v48, v64, s[0:1] offset:2048
	global_load_dword v49, v64, s[0:1] offset:3072
	s_add_u32 s0, s0, 0x3300
	s_addc_u32 s1, s1, 0
	s_waitcnt vmcnt(32)
	v_lshlrev_b32_e32 v68, 16, v3
	v_and_b32_e32 v69, 0xffff0000, v3
	v_lshlrev_b32_e32 v70, 16, v4
	v_and_b32_e32 v71, 0xffff0000, v4
	v_lshlrev_b32_e32 v66, 16, v2
	v_and_b32_e32 v67, 0xffff0000, v2
	v_mul_f32_e32 v3, v68, v70
	v_mul_f32_e32 v4, v69, v71
	v_mul_f32_e32 v74, v52, v58
	v_mul_f32_e32 v75, v53, v59
	v_mul_f32_e32 v76, v54, v3
	v_mul_f32_e32 v77, v55, v4
	v_fma_f32 v74, v50, v56, v74
	v_fma_f32 v75, v51, v57, v75
	v_add_f32_e32 v74, v74, v76
	v_add_f32_e32 v75, v75, v77
	v_mul_f32_e32 v74, v74, v66
	v_mul_f32_e32 v75, v75, v67
	v_cvt_pk_bf16_f32 v2, v74, v75
	global_store_dword v64, v2, s[2:3]
	s_add_u32 s2, s2, 0x480
	s_addc_u32 s3, s3, 0
	v_lshlrev_b32_e32 v68, 16, v6
	v_and_b32_e32 v69, 0xffff0000, v6
	v_lshlrev_b32_e32 v70, 16, v7
	v_and_b32_e32 v71, 0xffff0000, v7
	v_lshlrev_b32_e32 v66, 16, v5
	v_and_b32_e32 v67, 0xffff0000, v5
	v_mul_f32_e32 v6, v68, v70
	v_mul_f32_e32 v7, v69, v71
	v_mul_f32_e32 v74, v52, v3
	v_mul_f32_e32 v75, v53, v4
	v_mul_f32_e32 v76, v54, v6
	v_mul_f32_e32 v77, v55, v7
	v_fma_f32 v74, v50, v58, v74
	v_fma_f32 v75, v51, v59, v75
	v_add_f32_e32 v74, v74, v76
	v_add_f32_e32 v75, v75, v77
	v_mul_f32_e32 v74, v74, v66
	v_mul_f32_e32 v75, v75, v67
	v_cvt_pk_bf16_f32 v5, v74, v75
	global_store_dword v64, v5, s[2:3]
	s_add_u32 s2, s2, 0x480
	s_addc_u32 s3, s3, 0
	v_lshlrev_b32_e32 v68, 16, v9
	v_and_b32_e32 v69, 0xffff0000, v9
	v_lshlrev_b32_e32 v70, 16, v10
	v_and_b32_e32 v71, 0xffff0000, v10
	v_lshlrev_b32_e32 v66, 16, v8
	v_and_b32_e32 v67, 0xffff0000, v8
	v_mul_f32_e32 v9, v68, v70
	v_mul_f32_e32 v10, v69, v71
	v_mul_f32_e32 v74, v52, v6
	v_mul_f32_e32 v75, v53, v7
	v_mul_f32_e32 v76, v54, v9
	v_mul_f32_e32 v77, v55, v10
	v_fma_f32 v74, v50, v3, v74
	v_fma_f32 v75, v51, v4, v75
	v_add_f32_e32 v74, v74, v76
	v_add_f32_e32 v75, v75, v77
	v_mul_f32_e32 v74, v74, v66
	v_mul_f32_e32 v75, v75, v67
	v_cvt_pk_bf16_f32 v8, v74, v75
	global_store_dword v64, v8, s[2:3]
	s_add_u32 s2, s2, 0x480
	s_addc_u32 s3, s3, 0
	v_lshlrev_b32_e32 v68, 16, v12
	v_and_b32_e32 v69, 0xffff0000, v12
	v_lshlrev_b32_e32 v70, 16, v13
	v_and_b32_e32 v71, 0xffff0000, v13
	v_lshlrev_b32_e32 v66, 16, v11
	v_and_b32_e32 v67, 0xffff0000, v11
	v_mul_f32_e32 v12, v68, v70
	v_mul_f32_e32 v13, v69, v71
	v_mul_f32_e32 v74, v52, v9
	v_mul_f32_e32 v75, v53, v10
	v_mul_f32_e32 v76, v54, v12
	v_mul_f32_e32 v77, v55, v13
	v_fma_f32 v74, v50, v6, v74
	v_fma_f32 v75, v51, v7, v75
	v_add_f32_e32 v74, v74, v76
	v_add_f32_e32 v75, v75, v77
	v_mul_f32_e32 v74, v74, v66
	v_mul_f32_e32 v75, v75, v67
	v_cvt_pk_bf16_f32 v11, v74, v75
	global_store_dword v64, v11, s[2:3]
	s_add_u32 s2, s2, 0x480
	s_addc_u32 s3, s3, 0
	v_lshlrev_b32_e32 v68, 16, v15
	v_and_b32_e32 v69, 0xffff0000, v15
	v_lshlrev_b32_e32 v70, 16, v16
	v_and_b32_e32 v71, 0xffff0000, v16
	v_lshlrev_b32_e32 v66, 16, v14
	v_and_b32_e32 v67, 0xffff0000, v14
	v_mul_f32_e32 v15, v68, v70
	v_mul_f32_e32 v16, v69, v71
	v_mul_f32_e32 v74, v52, v12
	v_mul_f32_e32 v75, v53, v13
	v_mul_f32_e32 v76, v54, v15
	v_mul_f32_e32 v77, v55, v16
	v_fma_f32 v74, v50, v9, v74
	v_fma_f32 v75, v51, v10, v75
	v_add_f32_e32 v74, v74, v76
	v_add_f32_e32 v75, v75, v77
	v_mul_f32_e32 v74, v74, v66
	v_mul_f32_e32 v75, v75, v67
	v_cvt_pk_bf16_f32 v14, v74, v75
	global_store_dword v64, v14, s[2:3]
	s_add_u32 s2, s2, 0x480
	s_addc_u32 s3, s3, 0
	v_lshlrev_b32_e32 v68, 16, v18
	v_and_b32_e32 v69, 0xffff0000, v18
	v_lshlrev_b32_e32 v70, 16, v19
	v_and_b32_e32 v71, 0xffff0000, v19
	v_lshlrev_b32_e32 v66, 16, v17
	v_and_b32_e32 v67, 0xffff0000, v17
	v_mul_f32_e32 v18, v68, v70
	v_mul_f32_e32 v19, v69, v71
	v_mul_f32_e32 v74, v52, v15
	v_mul_f32_e32 v75, v53, v16
	v_mul_f32_e32 v76, v54, v18
	v_mul_f32_e32 v77, v55, v19
	v_fma_f32 v74, v50, v12, v74
	v_fma_f32 v75, v51, v13, v75
	v_add_f32_e32 v74, v74, v76
	v_add_f32_e32 v75, v75, v77
	v_mul_f32_e32 v74, v74, v66
	v_mul_f32_e32 v75, v75, v67
	v_cvt_pk_bf16_f32 v17, v74, v75
	global_store_dword v64, v17, s[2:3]
	s_add_u32 s2, s2, 0x480
	s_addc_u32 s3, s3, 0
	v_lshlrev_b32_e32 v68, 16, v21
	v_and_b32_e32 v69, 0xffff0000, v21
	v_lshlrev_b32_e32 v70, 16, v22
	v_and_b32_e32 v71, 0xffff0000, v22
	v_lshlrev_b32_e32 v66, 16, v20
	v_and_b32_e32 v67, 0xffff0000, v20
	v_mul_f32_e32 v21, v68, v70
	v_mul_f32_e32 v22, v69, v71
	v_mul_f32_e32 v74, v52, v18
	v_mul_f32_e32 v75, v53, v19
	v_mul_f32_e32 v76, v54, v21
	v_mul_f32_e32 v77, v55, v22
	v_fma_f32 v74, v50, v15, v74
	v_fma_f32 v75, v51, v16, v75
	v_add_f32_e32 v74, v74, v76
	v_add_f32_e32 v75, v75, v77
	v_mul_f32_e32 v74, v74, v66
	v_mul_f32_e32 v75, v75, v67
	v_cvt_pk_bf16_f32 v20, v74, v75
	global_store_dword v64, v20, s[2:3]
	s_add_u32 s2, s2, 0x480
	s_addc_u32 s3, s3, 0
	v_lshlrev_b32_e32 v68, 16, v24
	v_and_b32_e32 v69, 0xffff0000, v24
	v_lshlrev_b32_e32 v70, 16, v25
	v_and_b32_e32 v71, 0xffff0000, v25
	v_lshlrev_b32_e32 v66, 16, v23
	v_and_b32_e32 v67, 0xffff0000, v23
	v_mul_f32_e32 v24, v68, v70
	v_mul_f32_e32 v25, v69, v71
	v_mul_f32_e32 v74, v52, v21
	v_mul_f32_e32 v75, v53, v22
	v_mul_f32_e32 v76, v54, v24
	v_mul_f32_e32 v77, v55, v25
	v_fma_f32 v74, v50, v18, v74
	v_fma_f32 v75, v51, v19, v75
	v_add_f32_e32 v74, v74, v76
	v_add_f32_e32 v75, v75, v77
	v_mul_f32_e32 v74, v74, v66
	v_mul_f32_e32 v75, v75, v67
	v_cvt_pk_bf16_f32 v23, v74, v75
	global_store_dword v64, v23, s[2:3]
	s_add_u32 s2, s2, 0x480
	s_addc_u32 s3, s3, 0
	v_mov_b32_e32 v56, v21
	v_mov_b32_e32 v57, v22
	v_mov_b32_e32 v58, v24
	v_mov_b32_e32 v59, v25
	global_load_dword v2, v64, s[0:1] offset:1024
	global_load_dword v3, v64, s[0:1] offset:2048
	global_load_dword v4, v64, s[0:1] offset:3072
	s_add_u32 s0, s0, 0x3300
	s_addc_u32 s1, s1, 0
	global_load_dword v5, v64, s[0:1] offset:1024
	global_load_dword v6, v64, s[0:1] offset:2048
	global_load_dword v7, v64, s[0:1] offset:3072
	s_add_u32 s0, s0, 0x3300
	s_addc_u32 s1, s1, 0
	global_load_dword v8, v64, s[0:1] offset:1024
	global_load_dword v9, v64, s[0:1] offset:2048
	global_load_dword v10, v64, s[0:1] offset:3072
	s_add_u32 s0, s0, 0x3300
	s_addc_u32 s1, s1, 0
	global_load_dword v11, v64, s[0:1] offset:1024
	global_load_dword v12, v64, s[0:1] offset:2048
	global_load_dword v13, v64, s[0:1] offset:3072
	s_add_u32 s0, s0, 0x3300
	s_addc_u32 s1, s1, 0
	global_load_dword v14, v64, s[0:1] offset:1024
	global_load_dword v15, v64, s[0:1] offset:2048
	global_load_dword v16, v64, s[0:1] offset:3072
	s_add_u32 s0, s0, 0x3300
	s_addc_u32 s1, s1, 0
	global_load_dword v17, v64, s[0:1] offset:1024
	global_load_dword v18, v64, s[0:1] offset:2048
	global_load_dword v19, v64, s[0:1] offset:3072
	s_add_u32 s0, s0, 0x3300
	s_addc_u32 s1, s1, 0
	global_load_dword v20, v64, s[0:1] offset:1024
	global_load_dword v21, v64, s[0:1] offset:2048
	global_load_dword v22, v64, s[0:1] offset:3072
	s_add_u32 s0, s0, 0x3300
	s_addc_u32 s1, s1, 0
	global_load_dword v23, v64, s[0:1] offset:1024
	global_load_dword v24, v64, s[0:1] offset:2048
	global_load_dword v25, v64, s[0:1] offset:3072
	s_add_u32 s0, s0, 0x3300
	s_addc_u32 s1, s1, 0
	s_waitcnt vmcnt(32)
	v_lshlrev_b32_e32 v68, 16, v27
	v_and_b32_e32 v69, 0xffff0000, v27
	v_lshlrev_b32_e32 v70, 16, v28
	v_and_b32_e32 v71, 0xffff0000, v28
	v_lshlrev_b32_e32 v66, 16, v26
	v_and_b32_e32 v67, 0xffff0000, v26
	v_mul_f32_e32 v27, v68, v70
	v_mul_f32_e32 v28, v69, v71
	v_mul_f32_e32 v74, v52, v58
	v_mul_f32_e32 v75, v53, v59
	v_mul_f32_e32 v76, v54, v27
	v_mul_f32_e32 v77, v55, v28
	v_fma_f32 v74, v50, v56, v74
	v_fma_f32 v75, v51, v57, v75
	v_add_f32_e32 v74, v74, v76
	v_add_f32_e32 v75, v75, v77
	v_mul_f32_e32 v74, v74, v66
	v_mul_f32_e32 v75, v75, v67
	v_cvt_pk_bf16_f32 v26, v74, v75
	global_store_dword v64, v26, s[2:3]
	s_add_u32 s2, s2, 0x480
	s_addc_u32 s3, s3, 0
	v_lshlrev_b32_e32 v68, 16, v30
	v_and_b32_e32 v69, 0xffff0000, v30
	v_lshlrev_b32_e32 v70, 16, v31
	v_and_b32_e32 v71, 0xffff0000, v31
	v_lshlrev_b32_e32 v66, 16, v29
	v_and_b32_e32 v67, 0xffff0000, v29
	v_mul_f32_e32 v30, v68, v70
	v_mul_f32_e32 v31, v69, v71
	v_mul_f32_e32 v74, v52, v27
	v_mul_f32_e32 v75, v53, v28
	v_mul_f32_e32 v76, v54, v30
	v_mul_f32_e32 v77, v55, v31
	v_fma_f32 v74, v50, v58, v74
	v_fma_f32 v75, v51, v59, v75
	v_add_f32_e32 v74, v74, v76
	v_add_f32_e32 v75, v75, v77
	v_mul_f32_e32 v74, v74, v66
	v_mul_f32_e32 v75, v75, v67
	v_cvt_pk_bf16_f32 v29, v74, v75
	global_store_dword v64, v29, s[2:3]
	s_add_u32 s2, s2, 0x480
	s_addc_u32 s3, s3, 0
	v_lshlrev_b32_e32 v68, 16, v33
	v_and_b32_e32 v69, 0xffff0000, v33
	v_lshlrev_b32_e32 v70, 16, v34
	v_and_b32_e32 v71, 0xffff0000, v34
	v_lshlrev_b32_e32 v66, 16, v32
	v_and_b32_e32 v67, 0xffff0000, v32
	v_mul_f32_e32 v33, v68, v70
	v_mul_f32_e32 v34, v69, v71
	v_mul_f32_e32 v74, v52, v30
	v_mul_f32_e32 v75, v53, v31
	v_mul_f32_e32 v76, v54, v33
	v_mul_f32_e32 v77, v55, v34
	v_fma_f32 v74, v50, v27, v74
	v_fma_f32 v75, v51, v28, v75
	v_add_f32_e32 v74, v74, v76
	v_add_f32_e32 v75, v75, v77
	v_mul_f32_e32 v74, v74, v66
	v_mul_f32_e32 v75, v75, v67
	v_cvt_pk_bf16_f32 v32, v74, v75
	global_store_dword v64, v32, s[2:3]
	s_add_u32 s2, s2, 0x480
	s_addc_u32 s3, s3, 0
	v_lshlrev_b32_e32 v68, 16, v36
	v_and_b32_e32 v69, 0xffff0000, v36
	v_lshlrev_b32_e32 v70, 16, v37
	v_and_b32_e32 v71, 0xffff0000, v37
	v_lshlrev_b32_e32 v66, 16, v35
	v_and_b32_e32 v67, 0xffff0000, v35
	v_mul_f32_e32 v36, v68, v70
	v_mul_f32_e32 v37, v69, v71
	v_mul_f32_e32 v74, v52, v33
	v_mul_f32_e32 v75, v53, v34
	v_mul_f32_e32 v76, v54, v36
	v_mul_f32_e32 v77, v55, v37
	v_fma_f32 v74, v50, v30, v74
	v_fma_f32 v75, v51, v31, v75
	v_add_f32_e32 v74, v74, v76
	v_add_f32_e32 v75, v75, v77
	v_mul_f32_e32 v74, v74, v66
	v_mul_f32_e32 v75, v75, v67
	v_cvt_pk_bf16_f32 v35, v74, v75
	global_store_dword v64, v35, s[2:3]
	s_add_u32 s2, s2, 0x480
	s_addc_u32 s3, s3, 0
	v_lshlrev_b32_e32 v68, 16, v39
	v_and_b32_e32 v69, 0xffff0000, v39
	v_lshlrev_b32_e32 v70, 16, v40
	v_and_b32_e32 v71, 0xffff0000, v40
	v_lshlrev_b32_e32 v66, 16, v38
	v_and_b32_e32 v67, 0xffff0000, v38
	v_mul_f32_e32 v39, v68, v70
	v_mul_f32_e32 v40, v69, v71
	v_mul_f32_e32 v74, v52, v36
	v_mul_f32_e32 v75, v53, v37
	v_mul_f32_e32 v76, v54, v39
	v_mul_f32_e32 v77, v55, v40
	v_fma_f32 v74, v50, v33, v74
	v_fma_f32 v75, v51, v34, v75
	v_add_f32_e32 v74, v74, v76
	v_add_f32_e32 v75, v75, v77
	v_mul_f32_e32 v74, v74, v66
	v_mul_f32_e32 v75, v75, v67
	v_cvt_pk_bf16_f32 v38, v74, v75
	global_store_dword v64, v38, s[2:3]
	s_add_u32 s2, s2, 0x480
	s_addc_u32 s3, s3, 0
	v_lshlrev_b32_e32 v68, 16, v42
	v_and_b32_e32 v69, 0xffff0000, v42
	v_lshlrev_b32_e32 v70, 16, v43
	v_and_b32_e32 v71, 0xffff0000, v43
	v_lshlrev_b32_e32 v66, 16, v41
	v_and_b32_e32 v67, 0xffff0000, v41
	v_mul_f32_e32 v42, v68, v70
	v_mul_f32_e32 v43, v69, v71
	v_mul_f32_e32 v74, v52, v39
	v_mul_f32_e32 v75, v53, v40
	v_mul_f32_e32 v76, v54, v42
	v_mul_f32_e32 v77, v55, v43
	v_fma_f32 v74, v50, v36, v74
	v_fma_f32 v75, v51, v37, v75
	v_add_f32_e32 v74, v74, v76
	v_add_f32_e32 v75, v75, v77
	v_mul_f32_e32 v74, v74, v66
	v_mul_f32_e32 v75, v75, v67
	v_cvt_pk_bf16_f32 v41, v74, v75
	global_store_dword v64, v41, s[2:3]
	s_add_u32 s2, s2, 0x480
	s_addc_u32 s3, s3, 0
	v_lshlrev_b32_e32 v68, 16, v45
	v_and_b32_e32 v69, 0xffff0000, v45
	v_lshlrev_b32_e32 v70, 16, v46
	v_and_b32_e32 v71, 0xffff0000, v46
	v_lshlrev_b32_e32 v66, 16, v44
	v_and_b32_e32 v67, 0xffff0000, v44
	v_mul_f32_e32 v45, v68, v70
	v_mul_f32_e32 v46, v69, v71
	v_mul_f32_e32 v74, v52, v42
	v_mul_f32_e32 v75, v53, v43
	v_mul_f32_e32 v76, v54, v45
	v_mul_f32_e32 v77, v55, v46
	v_fma_f32 v74, v50, v39, v74
	v_fma_f32 v75, v51, v40, v75
	v_add_f32_e32 v74, v74, v76
	v_add_f32_e32 v75, v75, v77
	v_mul_f32_e32 v74, v74, v66
	v_mul_f32_e32 v75, v75, v67
	v_cvt_pk_bf16_f32 v44, v74, v75
	global_store_dword v64, v44, s[2:3]
	s_add_u32 s2, s2, 0x480
	s_addc_u32 s3, s3, 0
	v_lshlrev_b32_e32 v68, 16, v48
	v_and_b32_e32 v69, 0xffff0000, v48
	v_lshlrev_b32_e32 v70, 16, v49
	v_and_b32_e32 v71, 0xffff0000, v49
	v_lshlrev_b32_e32 v66, 16, v47
	v_and_b32_e32 v67, 0xffff0000, v47
	v_mul_f32_e32 v48, v68, v70
	v_mul_f32_e32 v49, v69, v71
	v_mul_f32_e32 v74, v52, v45
	v_mul_f32_e32 v75, v53, v46
	v_mul_f32_e32 v76, v54, v48
	v_mul_f32_e32 v77, v55, v49
	v_fma_f32 v74, v50, v42, v74
	v_fma_f32 v75, v51, v43, v75
	v_add_f32_e32 v74, v74, v76
	v_add_f32_e32 v75, v75, v77
	v_mul_f32_e32 v74, v74, v66
	v_mul_f32_e32 v75, v75, v67
	v_cvt_pk_bf16_f32 v47, v74, v75
	global_store_dword v64, v47, s[2:3]
	s_add_u32 s2, s2, 0x480
	s_addc_u32 s3, s3, 0
	v_mov_b32_e32 v56, v45
	v_mov_b32_e32 v57, v46
	v_mov_b32_e32 v58, v48
	v_mov_b32_e32 v59, v49
	global_load_dword v26, v64, s[0:1] offset:1024
	global_load_dword v27, v64, s[0:1] offset:2048
	global_load_dword v28, v64, s[0:1] offset:3072
	s_add_u32 s0, s0, 0x3300
	s_addc_u32 s1, s1, 0
	global_load_dword v29, v64, s[0:1] offset:1024
	global_load_dword v30, v64, s[0:1] offset:2048
	global_load_dword v31, v64, s[0:1] offset:3072
	s_add_u32 s0, s0, 0x3300
	s_addc_u32 s1, s1, 0
	global_load_dword v32, v64, s[0:1] offset:1024
	global_load_dword v33, v64, s[0:1] offset:2048
	global_load_dword v34, v64, s[0:1] offset:3072
	s_add_u32 s0, s0, 0x3300
	s_addc_u32 s1, s1, 0
	global_load_dword v35, v64, s[0:1] offset:1024
	global_load_dword v36, v64, s[0:1] offset:2048
	global_load_dword v37, v64, s[0:1] offset:3072
	s_add_u32 s0, s0, 0x3300
	s_addc_u32 s1, s1, 0
	global_load_dword v38, v64, s[0:1] offset:1024
	global_load_dword v39, v64, s[0:1] offset:2048
	global_load_dword v40, v64, s[0:1] offset:3072
	s_add_u32 s0, s0, 0x3300
	s_addc_u32 s1, s1, 0
	global_load_dword v41, v64, s[0:1] offset:1024
	global_load_dword v42, v64, s[0:1] offset:2048
	global_load_dword v43, v64, s[0:1] offset:3072
	s_add_u32 s0, s0, 0x3300
	s_addc_u32 s1, s1, 0
	global_load_dword v44, v64, s[0:1] offset:1024
	global_load_dword v45, v64, s[0:1] offset:2048
	global_load_dword v46, v64, s[0:1] offset:3072
	s_add_u32 s0, s0, 0x3300
	s_addc_u32 s1, s1, 0
	global_load_dword v47, v64, s[0:1] offset:1024
	global_load_dword v48, v64, s[0:1] offset:2048
	global_load_dword v49, v64, s[0:1] offset:3072
	s_add_u32 s0, s0, 0x3300
	s_addc_u32 s1, s1, 0
	s_waitcnt vmcnt(32)
	v_lshlrev_b32_e32 v68, 16, v3
	v_and_b32_e32 v69, 0xffff0000, v3
	v_lshlrev_b32_e32 v70, 16, v4
	v_and_b32_e32 v71, 0xffff0000, v4
	v_lshlrev_b32_e32 v66, 16, v2
	v_and_b32_e32 v67, 0xffff0000, v2
	v_mul_f32_e32 v3, v68, v70
	v_mul_f32_e32 v4, v69, v71
	v_mul_f32_e32 v74, v52, v58
	v_mul_f32_e32 v75, v53, v59
	v_mul_f32_e32 v76, v54, v3
	v_mul_f32_e32 v77, v55, v4
	v_fma_f32 v74, v50, v56, v74
	v_fma_f32 v75, v51, v57, v75
	v_add_f32_e32 v74, v74, v76
	v_add_f32_e32 v75, v75, v77
	v_mul_f32_e32 v74, v74, v66
	v_mul_f32_e32 v75, v75, v67
	v_cvt_pk_bf16_f32 v2, v74, v75
	global_store_dword v64, v2, s[2:3]
	s_add_u32 s2, s2, 0x480
	s_addc_u32 s3, s3, 0
	v_lshlrev_b32_e32 v68, 16, v6
	v_and_b32_e32 v69, 0xffff0000, v6
	v_lshlrev_b32_e32 v70, 16, v7
	v_and_b32_e32 v71, 0xffff0000, v7
	v_lshlrev_b32_e32 v66, 16, v5
	v_and_b32_e32 v67, 0xffff0000, v5
	v_mul_f32_e32 v6, v68, v70
	v_mul_f32_e32 v7, v69, v71
	v_mul_f32_e32 v74, v52, v3
	v_mul_f32_e32 v75, v53, v4
	v_mul_f32_e32 v76, v54, v6
	v_mul_f32_e32 v77, v55, v7
	v_fma_f32 v74, v50, v58, v74
	v_fma_f32 v75, v51, v59, v75
	v_add_f32_e32 v74, v74, v76
	v_add_f32_e32 v75, v75, v77
	v_mul_f32_e32 v74, v74, v66
	v_mul_f32_e32 v75, v75, v67
	v_cvt_pk_bf16_f32 v5, v74, v75
	global_store_dword v64, v5, s[2:3]
	s_add_u32 s2, s2, 0x480
	s_addc_u32 s3, s3, 0
	v_lshlrev_b32_e32 v68, 16, v9
	v_and_b32_e32 v69, 0xffff0000, v9
	v_lshlrev_b32_e32 v70, 16, v10
	v_and_b32_e32 v71, 0xffff0000, v10
	v_lshlrev_b32_e32 v66, 16, v8
	v_and_b32_e32 v67, 0xffff0000, v8
	v_mul_f32_e32 v9, v68, v70
	v_mul_f32_e32 v10, v69, v71
	v_mul_f32_e32 v74, v52, v6
	v_mul_f32_e32 v75, v53, v7
	v_mul_f32_e32 v76, v54, v9
	v_mul_f32_e32 v77, v55, v10
	v_fma_f32 v74, v50, v3, v74
	v_fma_f32 v75, v51, v4, v75
	v_add_f32_e32 v74, v74, v76
	v_add_f32_e32 v75, v75, v77
	v_mul_f32_e32 v74, v74, v66
	v_mul_f32_e32 v75, v75, v67
	v_cvt_pk_bf16_f32 v8, v74, v75
	global_store_dword v64, v8, s[2:3]
	s_add_u32 s2, s2, 0x480
	s_addc_u32 s3, s3, 0
	v_lshlrev_b32_e32 v68, 16, v12
	v_and_b32_e32 v69, 0xffff0000, v12
	v_lshlrev_b32_e32 v70, 16, v13
	v_and_b32_e32 v71, 0xffff0000, v13
	v_lshlrev_b32_e32 v66, 16, v11
	v_and_b32_e32 v67, 0xffff0000, v11
	v_mul_f32_e32 v12, v68, v70
	v_mul_f32_e32 v13, v69, v71
	v_mul_f32_e32 v74, v52, v9
	v_mul_f32_e32 v75, v53, v10
	v_mul_f32_e32 v76, v54, v12
	v_mul_f32_e32 v77, v55, v13
	v_fma_f32 v74, v50, v6, v74
	v_fma_f32 v75, v51, v7, v75
	v_add_f32_e32 v74, v74, v76
	v_add_f32_e32 v75, v75, v77
	v_mul_f32_e32 v74, v74, v66
	v_mul_f32_e32 v75, v75, v67
	v_cvt_pk_bf16_f32 v11, v74, v75
	global_store_dword v64, v11, s[2:3]
	s_add_u32 s2, s2, 0x480
	s_addc_u32 s3, s3, 0
	v_lshlrev_b32_e32 v68, 16, v15
	v_and_b32_e32 v69, 0xffff0000, v15
	v_lshlrev_b32_e32 v70, 16, v16
	v_and_b32_e32 v71, 0xffff0000, v16
	v_lshlrev_b32_e32 v66, 16, v14
	v_and_b32_e32 v67, 0xffff0000, v14
	v_mul_f32_e32 v15, v68, v70
	v_mul_f32_e32 v16, v69, v71
	v_mul_f32_e32 v74, v52, v12
	v_mul_f32_e32 v75, v53, v13
	v_mul_f32_e32 v76, v54, v15
	v_mul_f32_e32 v77, v55, v16
	v_fma_f32 v74, v50, v9, v74
	v_fma_f32 v75, v51, v10, v75
	v_add_f32_e32 v74, v74, v76
	v_add_f32_e32 v75, v75, v77
	v_mul_f32_e32 v74, v74, v66
	v_mul_f32_e32 v75, v75, v67
	v_cvt_pk_bf16_f32 v14, v74, v75
	global_store_dword v64, v14, s[2:3]
	s_add_u32 s2, s2, 0x480
	s_addc_u32 s3, s3, 0
	v_lshlrev_b32_e32 v68, 16, v18
	v_and_b32_e32 v69, 0xffff0000, v18
	v_lshlrev_b32_e32 v70, 16, v19
	v_and_b32_e32 v71, 0xffff0000, v19
	v_lshlrev_b32_e32 v66, 16, v17
	v_and_b32_e32 v67, 0xffff0000, v17
	v_mul_f32_e32 v18, v68, v70
	v_mul_f32_e32 v19, v69, v71
	v_mul_f32_e32 v74, v52, v15
	v_mul_f32_e32 v75, v53, v16
	v_mul_f32_e32 v76, v54, v18
	v_mul_f32_e32 v77, v55, v19
	v_fma_f32 v74, v50, v12, v74
	v_fma_f32 v75, v51, v13, v75
	v_add_f32_e32 v74, v74, v76
	v_add_f32_e32 v75, v75, v77
	v_mul_f32_e32 v74, v74, v66
	v_mul_f32_e32 v75, v75, v67
	v_cvt_pk_bf16_f32 v17, v74, v75
	global_store_dword v64, v17, s[2:3]
	s_add_u32 s2, s2, 0x480
	s_addc_u32 s3, s3, 0
	v_lshlrev_b32_e32 v68, 16, v21
	v_and_b32_e32 v69, 0xffff0000, v21
	v_lshlrev_b32_e32 v70, 16, v22
	v_and_b32_e32 v71, 0xffff0000, v22
	v_lshlrev_b32_e32 v66, 16, v20
	v_and_b32_e32 v67, 0xffff0000, v20
	v_mul_f32_e32 v21, v68, v70
	v_mul_f32_e32 v22, v69, v71
	v_mul_f32_e32 v74, v52, v18
	v_mul_f32_e32 v75, v53, v19
	v_mul_f32_e32 v76, v54, v21
	v_mul_f32_e32 v77, v55, v22
	v_fma_f32 v74, v50, v15, v74
	v_fma_f32 v75, v51, v16, v75
	v_add_f32_e32 v74, v74, v76
	v_add_f32_e32 v75, v75, v77
	v_mul_f32_e32 v74, v74, v66
	v_mul_f32_e32 v75, v75, v67
	v_cvt_pk_bf16_f32 v20, v74, v75
	global_store_dword v64, v20, s[2:3]
	s_add_u32 s2, s2, 0x480
	s_addc_u32 s3, s3, 0
	v_lshlrev_b32_e32 v68, 16, v24
	v_and_b32_e32 v69, 0xffff0000, v24
	v_lshlrev_b32_e32 v70, 16, v25
	v_and_b32_e32 v71, 0xffff0000, v25
	v_lshlrev_b32_e32 v66, 16, v23
	v_and_b32_e32 v67, 0xffff0000, v23
	v_mul_f32_e32 v24, v68, v70
	v_mul_f32_e32 v25, v69, v71
	v_mul_f32_e32 v74, v52, v21
	v_mul_f32_e32 v75, v53, v22
	v_mul_f32_e32 v76, v54, v24
	v_mul_f32_e32 v77, v55, v25
	v_fma_f32 v74, v50, v18, v74
	v_fma_f32 v75, v51, v19, v75
	v_add_f32_e32 v74, v74, v76
	v_add_f32_e32 v75, v75, v77
	v_mul_f32_e32 v74, v74, v66
	v_mul_f32_e32 v75, v75, v67
	v_cvt_pk_bf16_f32 v23, v74, v75
	global_store_dword v64, v23, s[2:3]
	s_add_u32 s2, s2, 0x480
	s_addc_u32 s3, s3, 0
	v_mov_b32_e32 v56, v21
	v_mov_b32_e32 v57, v22
	v_mov_b32_e32 v58, v24
	v_mov_b32_e32 v59, v25
	s_waitcnt vmcnt(8)
	v_lshlrev_b32_e32 v68, 16, v27
	v_and_b32_e32 v69, 0xffff0000, v27
	v_lshlrev_b32_e32 v70, 16, v28
	v_and_b32_e32 v71, 0xffff0000, v28
	v_lshlrev_b32_e32 v66, 16, v26
	v_and_b32_e32 v67, 0xffff0000, v26
	v_mul_f32_e32 v27, v68, v70
	v_mul_f32_e32 v28, v69, v71
	v_mul_f32_e32 v74, v52, v58
	v_mul_f32_e32 v75, v53, v59
	v_mul_f32_e32 v76, v54, v27
	v_mul_f32_e32 v77, v55, v28
	v_fma_f32 v74, v50, v56, v74
	v_fma_f32 v75, v51, v57, v75
	v_add_f32_e32 v74, v74, v76
	v_add_f32_e32 v75, v75, v77
	v_mul_f32_e32 v74, v74, v66
	v_mul_f32_e32 v75, v75, v67
	v_cvt_pk_bf16_f32 v26, v74, v75
	global_store_dword v64, v26, s[2:3]
	s_add_u32 s2, s2, 0x480
	s_addc_u32 s3, s3, 0
	v_lshlrev_b32_e32 v68, 16, v30
	v_and_b32_e32 v69, 0xffff0000, v30
	v_lshlrev_b32_e32 v70, 16, v31
	v_and_b32_e32 v71, 0xffff0000, v31
	v_lshlrev_b32_e32 v66, 16, v29
	v_and_b32_e32 v67, 0xffff0000, v29
	v_mul_f32_e32 v30, v68, v70
	v_mul_f32_e32 v31, v69, v71
	v_mul_f32_e32 v74, v52, v27
	v_mul_f32_e32 v75, v53, v28
	v_mul_f32_e32 v76, v54, v30
	v_mul_f32_e32 v77, v55, v31
	v_fma_f32 v74, v50, v58, v74
	v_fma_f32 v75, v51, v59, v75
	v_add_f32_e32 v74, v74, v76
	v_add_f32_e32 v75, v75, v77
	v_mul_f32_e32 v74, v74, v66
	v_mul_f32_e32 v75, v75, v67
	v_cvt_pk_bf16_f32 v29, v74, v75
	global_store_dword v64, v29, s[2:3]
	s_add_u32 s2, s2, 0x480
	s_addc_u32 s3, s3, 0
	v_lshlrev_b32_e32 v68, 16, v33
	v_and_b32_e32 v69, 0xffff0000, v33
	v_lshlrev_b32_e32 v70, 16, v34
	v_and_b32_e32 v71, 0xffff0000, v34
	v_lshlrev_b32_e32 v66, 16, v32
	v_and_b32_e32 v67, 0xffff0000, v32
	v_mul_f32_e32 v33, v68, v70
	v_mul_f32_e32 v34, v69, v71
	v_mul_f32_e32 v74, v52, v30
	v_mul_f32_e32 v75, v53, v31
	v_mul_f32_e32 v76, v54, v33
	v_mul_f32_e32 v77, v55, v34
	v_fma_f32 v74, v50, v27, v74
	v_fma_f32 v75, v51, v28, v75
	v_add_f32_e32 v74, v74, v76
	v_add_f32_e32 v75, v75, v77
	v_mul_f32_e32 v74, v74, v66
	v_mul_f32_e32 v75, v75, v67
	v_cvt_pk_bf16_f32 v32, v74, v75
	global_store_dword v64, v32, s[2:3]
	s_add_u32 s2, s2, 0x480
	s_addc_u32 s3, s3, 0
	v_lshlrev_b32_e32 v68, 16, v36
	v_and_b32_e32 v69, 0xffff0000, v36
	v_lshlrev_b32_e32 v70, 16, v37
	v_and_b32_e32 v71, 0xffff0000, v37
	v_lshlrev_b32_e32 v66, 16, v35
	v_and_b32_e32 v67, 0xffff0000, v35
	v_mul_f32_e32 v36, v68, v70
	v_mul_f32_e32 v37, v69, v71
	v_mul_f32_e32 v74, v52, v33
	v_mul_f32_e32 v75, v53, v34
	v_mul_f32_e32 v76, v54, v36
	v_mul_f32_e32 v77, v55, v37
	v_fma_f32 v74, v50, v30, v74
	v_fma_f32 v75, v51, v31, v75
	v_add_f32_e32 v74, v74, v76
	v_add_f32_e32 v75, v75, v77
	v_mul_f32_e32 v74, v74, v66
	v_mul_f32_e32 v75, v75, v67
	v_cvt_pk_bf16_f32 v35, v74, v75
	global_store_dword v64, v35, s[2:3]
	s_add_u32 s2, s2, 0x480
	s_addc_u32 s3, s3, 0
	v_lshlrev_b32_e32 v68, 16, v39
	v_and_b32_e32 v69, 0xffff0000, v39
	v_lshlrev_b32_e32 v70, 16, v40
	v_and_b32_e32 v71, 0xffff0000, v40
	v_lshlrev_b32_e32 v66, 16, v38
	v_and_b32_e32 v67, 0xffff0000, v38
	v_mul_f32_e32 v39, v68, v70
	v_mul_f32_e32 v40, v69, v71
	v_mul_f32_e32 v74, v52, v36
	v_mul_f32_e32 v75, v53, v37
	v_mul_f32_e32 v76, v54, v39
	v_mul_f32_e32 v77, v55, v40
	v_fma_f32 v74, v50, v33, v74
	v_fma_f32 v75, v51, v34, v75
	v_add_f32_e32 v74, v74, v76
	v_add_f32_e32 v75, v75, v77
	v_mul_f32_e32 v74, v74, v66
	v_mul_f32_e32 v75, v75, v67
	v_cvt_pk_bf16_f32 v38, v74, v75
	global_store_dword v64, v38, s[2:3]
	s_add_u32 s2, s2, 0x480
	s_addc_u32 s3, s3, 0
	v_lshlrev_b32_e32 v68, 16, v42
	v_and_b32_e32 v69, 0xffff0000, v42
	v_lshlrev_b32_e32 v70, 16, v43
	v_and_b32_e32 v71, 0xffff0000, v43
	v_lshlrev_b32_e32 v66, 16, v41
	v_and_b32_e32 v67, 0xffff0000, v41
	v_mul_f32_e32 v42, v68, v70
	v_mul_f32_e32 v43, v69, v71
	v_mul_f32_e32 v74, v52, v39
	v_mul_f32_e32 v75, v53, v40
	v_mul_f32_e32 v76, v54, v42
	v_mul_f32_e32 v77, v55, v43
	v_fma_f32 v74, v50, v36, v74
	v_fma_f32 v75, v51, v37, v75
	v_add_f32_e32 v74, v74, v76
	v_add_f32_e32 v75, v75, v77
	v_mul_f32_e32 v74, v74, v66
	v_mul_f32_e32 v75, v75, v67
	v_cvt_pk_bf16_f32 v41, v74, v75
	global_store_dword v64, v41, s[2:3]
	s_add_u32 s2, s2, 0x480
	s_addc_u32 s3, s3, 0
	v_lshlrev_b32_e32 v68, 16, v45
	v_and_b32_e32 v69, 0xffff0000, v45
	v_lshlrev_b32_e32 v70, 16, v46
	v_and_b32_e32 v71, 0xffff0000, v46
	v_lshlrev_b32_e32 v66, 16, v44
	v_and_b32_e32 v67, 0xffff0000, v44
	v_mul_f32_e32 v45, v68, v70
	v_mul_f32_e32 v46, v69, v71
	v_mul_f32_e32 v74, v52, v42
	v_mul_f32_e32 v75, v53, v43
	v_mul_f32_e32 v76, v54, v45
	v_mul_f32_e32 v77, v55, v46
	v_fma_f32 v74, v50, v39, v74
	v_fma_f32 v75, v51, v40, v75
	v_add_f32_e32 v74, v74, v76
	v_add_f32_e32 v75, v75, v77
	v_mul_f32_e32 v74, v74, v66
	v_mul_f32_e32 v75, v75, v67
	v_cvt_pk_bf16_f32 v44, v74, v75
	global_store_dword v64, v44, s[2:3]
	s_add_u32 s2, s2, 0x480
	s_addc_u32 s3, s3, 0
	v_lshlrev_b32_e32 v68, 16, v48
	v_and_b32_e32 v69, 0xffff0000, v48
	v_lshlrev_b32_e32 v70, 16, v49
	v_and_b32_e32 v71, 0xffff0000, v49
	v_lshlrev_b32_e32 v66, 16, v47
	v_and_b32_e32 v67, 0xffff0000, v47
	v_mul_f32_e32 v48, v68, v70
	v_mul_f32_e32 v49, v69, v71
	v_mul_f32_e32 v74, v52, v45
	v_mul_f32_e32 v75, v53, v46
	v_mul_f32_e32 v76, v54, v48
	v_mul_f32_e32 v77, v55, v49
	v_fma_f32 v74, v50, v42, v74
	v_fma_f32 v75, v51, v43, v75
	v_add_f32_e32 v74, v74, v76
	v_add_f32_e32 v75, v75, v77
	v_mul_f32_e32 v74, v74, v66
	v_mul_f32_e32 v75, v75, v67
	v_cvt_pk_bf16_f32 v47, v74, v75
	global_store_dword v64, v47, s[2:3]
	s_add_u32 s2, s2, 0x480
	s_addc_u32 s3, s3, 0
	v_mov_b32_e32 v56, v45
	v_mov_b32_e32 v57, v46
	v_mov_b32_e32 v58, v48
	v_mov_b32_e32 v59, v49
	s_branch .Lpp_done

.Lpp_done:
	v_mov_b32_e32 v0, v163
	s_barrier
	s_movk_i32 s0, 0x104
	v_mov_b32_e32 v0, v163
	s_add_i32 s4, s6, 0x80
	v_mov_b32_e32 v0, v163
	s_add_i32 s9, s6, 0xfffffe80
	v_mov_b32_e32 v0, v163
	s_nop 0
	v_mov_b32_e32 v0, v163
	s_nop 0
	v_lshlrev_b32_e32 v2, 3, v0
	v_and_b32_e32 v2, 56, v2
	v_and_b32_e32 v4, 63, v0
	v_ashrrev_i32_e32 v6, 6, v0
	v_and_b32_e32 v8, 31, v0
	v_ashrrev_i32_e32 v9, 3, v0
	v_lshlrev_b32_e32 v0, 1, v2
	v_lshlrev_b32_e32 v10, 2, v2
	v_lshl_add_u64 v[2:3], s[56:57], 0, v[0:1]
	v_lshlrev_b32_e32 v0, 2, v6
	v_mad_u32_u24 v0, v4, s0, v0
	v_mul_lo_u32 v20, v9, s0
	s_lshl_b32 s0, s6, 6
	v_cmp_gt_u32_e32 vcc, 32, v4
	s_add_i32 s5, s0, 0x2000
	s_lshr_b32 s0, s4, 4
	v_cndmask_b32_e64 v7, v203, 0, vcc
	v_add_u32_e32 v11, 32, v6
	v_add_u32_e32 v12, 36, v6
	v_add_u32_e32 v13, 40, v6
	v_add_u32_e32 v14, 44, v6
	v_add_u32_e32 v15, 48, v6
	v_add_u32_e32 v16, 52, v6
	v_add_u32_e32 v17, 56, v6
	v_add_u32_e32 v18, 60, v6
	v_sub_u32_e32 v19, 0x1600, v9
	v_sub_u32_e32 v21, 0x15e0, v9
	s_lshl_b32 s7, s0, 5
	s_lshl_b32 s8, s0, 6
	s_branch .LBB0_367
